# in_proj GEMM: row rstd prefetched before each unit K-loop (same change as for q-proj/FFN-up)
# speedup vs baseline: 1.0006x; 1.0006x over previous
;     __device__ __forceinline__ void operator()(const f32x4 (&acc)[2][2][4][2], const Unit& u, int wr, int wc, int fr_, int fq_) const {
;     ...
;         const int col0 = colt + wc * 32 + 8 * fq, rowb = u.pm * BM + wr * 64 + fr;
;         float rs[2][4];
; #pragma unroll
;         for (int ai = 0; ai < 2; ++ai)
; #pragma unroll
;             for (int m = 0; m < 4; ++m) rs[ai][m] = rstd[rowb + ai * HALF + m * 16];
; template <class Epi, class Sched, bool ALIGN_EPI = false, bool SP2 = false>
; __device__ __forceinline__ void gemm_phase(PG8_LAS unsigned char* lds, const Gemm g, const Sched& S, const Epi& E) {
;     ...
; #pragma unroll
;         for (int a = 0; a < 2; ++a)
; #pragma unroll
;             for (int b = 0; b < 2; ++b)
; #pragma unroll
;                 for (int m = 0; m < 4; ++m)
; #pragma unroll
;                     for (int n = 0; n < 2; ++n) acc[a][b][m][n] = (f32x4){0.f, 0.f, 0.f, 0.f};
.LBB0_812:
	s_ashr_i32 s39, s38, 31
	s_lshl_b64 s[2:3], s[38:39], 19
	s_add_u32 s40, s18, s2
	s_addc_u32 s41, s19, s3
	s_and_b64 s[2:3], s[4:5], exec
	s_cselect_b32 s9, s41, s47
	s_cselect_b32 s39, s40, s46
	s_ashr_i32 s37, s36, 31
	s_lshl_b64 s[2:3], s[36:37], 19
	s_add_u32 s42, s20, s2
	s_addc_u32 s43, s21, s3
	s_and_b64 s[2:3], s[4:5], exec
	s_cselect_b32 s37, s43, s7
	s_cselect_b32 s45, s42, s6
	s_add_u32 s2, s46, 0x40080
	s_addc_u32 s3, s47, 0
	s_add_u32 s48, s6, 0x100
	v_mov_b32_e32 v0, 0
	s_addc_u32 s49, s7, 0
	s_mov_b32 s77, -2
	v_mov_b32_e32 v1, v0
	v_mov_b32_e32 v2, v0
	v_mov_b32_e32 v3, v0
	s_waitcnt lgkmcnt(0)
	v_mov_b32_e32 v4, v0
	v_mov_b32_e32 v5, v0
	v_mov_b32_e32 v6, v0
	v_mov_b32_e32 v7, v0
	v_mov_b32_e32 v16, v0
	v_mov_b32_e32 v17, v0
	v_mov_b32_e32 v18, v0
	v_mov_b32_e32 v19, v0
	v_mov_b32_e32 v20, v0
	v_mov_b32_e32 v21, v0
	v_mov_b32_e32 v22, v0
	v_mov_b32_e32 v23, v0
	v_mov_b32_e32 v32, v0
	v_mov_b32_e32 v33, v0
	v_mov_b32_e32 v34, v0
	v_mov_b32_e32 v35, v0
	v_mov_b32_e32 v36, v0
	v_mov_b32_e32 v37, v0
	v_mov_b32_e32 v38, v0
	v_mov_b32_e32 v39, v0
	v_mov_b32_e32 v48, v0
	v_mov_b32_e32 v49, v0
	v_mov_b32_e32 v50, v0
	v_mov_b32_e32 v51, v0
	v_mov_b32_e32 v52, v0
	v_mov_b32_e32 v53, v0
	v_mov_b32_e32 v54, v0
	v_mov_b32_e32 v55, v0
	v_mov_b32_e32 v8, v0
	v_mov_b32_e32 v9, v0
	v_mov_b32_e32 v10, v0
	v_mov_b32_e32 v11, v0
	v_mov_b32_e32 v12, v0
	v_mov_b32_e32 v13, v0
	v_mov_b32_e32 v14, v0
	v_mov_b32_e32 v15, v0
	v_mov_b32_e32 v24, v0
	v_mov_b32_e32 v25, v0
	v_mov_b32_e32 v26, v0
	v_mov_b32_e32 v27, v0
	v_mov_b32_e32 v28, v0
	v_mov_b32_e32 v29, v0
	v_mov_b32_e32 v30, v0
	v_mov_b32_e32 v31, v0
	v_mov_b32_e32 v40, v0
	v_mov_b32_e32 v41, v0
	v_mov_b32_e32 v42, v0
	v_mov_b32_e32 v43, v0
	v_mov_b32_e32 v44, v0
	v_mov_b32_e32 v45, v0
	v_mov_b32_e32 v46, v0
	v_mov_b32_e32 v47, v0
	v_mov_b32_e32 v56, v0
	v_mov_b32_e32 v57, v0
	v_mov_b32_e32 v58, v0
	v_mov_b32_e32 v59, v0
	v_mov_b32_e32 v60, v0
	v_mov_b32_e32 v61, v0
	v_mov_b32_e32 v62, v0
	v_mov_b32_e32 v63, v0
	v_mov_b32_e32 v64, v0
	v_mov_b32_e32 v65, v0
	v_mov_b32_e32 v66, v0
	v_mov_b32_e32 v67, v0
	v_mov_b32_e32 v68, v0
	v_mov_b32_e32 v69, v0
	v_mov_b32_e32 v70, v0
	v_mov_b32_e32 v71, v0
	v_mov_b32_e32 v80, v0
	v_mov_b32_e32 v81, v0
	v_mov_b32_e32 v82, v0
	v_mov_b32_e32 v83, v0
	v_mov_b32_e32 v84, v0
	v_mov_b32_e32 v85, v0
	v_mov_b32_e32 v86, v0
	v_mov_b32_e32 v87, v0
	v_mov_b32_e32 v96, v0
	v_mov_b32_e32 v97, v0
	v_mov_b32_e32 v98, v0
	v_mov_b32_e32 v99, v0
	v_mov_b32_e32 v100, v0
	v_mov_b32_e32 v101, v0
	v_mov_b32_e32 v102, v0
	v_mov_b32_e32 v103, v0
	v_mov_b32_e32 v112, v0
	v_mov_b32_e32 v113, v0
	v_mov_b32_e32 v114, v0
	v_mov_b32_e32 v115, v0
	v_mov_b32_e32 v116, v0
	v_mov_b32_e32 v117, v0
	v_mov_b32_e32 v118, v0
	v_mov_b32_e32 v119, v0
	v_mov_b32_e32 v72, v0
	v_mov_b32_e32 v73, v0
	v_mov_b32_e32 v74, v0
	v_mov_b32_e32 v75, v0
	v_mov_b32_e32 v76, v0
	v_mov_b32_e32 v77, v0
	v_mov_b32_e32 v78, v0
	v_mov_b32_e32 v79, v0
	v_mov_b32_e32 v88, v0
	v_mov_b32_e32 v89, v0
	v_mov_b32_e32 v90, v0
	v_mov_b32_e32 v91, v0
	v_mov_b32_e32 v92, v0
	v_mov_b32_e32 v93, v0
	v_mov_b32_e32 v94, v0
	v_mov_b32_e32 v95, v0
	v_mov_b32_e32 v104, v0
	v_mov_b32_e32 v105, v0
	v_mov_b32_e32 v106, v0
	v_mov_b32_e32 v107, v0
	v_mov_b32_e32 v108, v0
	v_mov_b32_e32 v109, v0
	v_mov_b32_e32 v110, v0
	v_mov_b32_e32 v111, v0
	v_mov_b32_e32 v120, v0
	v_mov_b32_e32 v121, v0
	v_mov_b32_e32 v122, v0
	v_mov_b32_e32 v123, v0
	v_mov_b32_e32 v124, v0
	v_mov_b32_e32 v125, v0
	v_mov_b32_e32 v126, v0
	v_mov_b32_e32 v127, v0
	s_lshl_b32 s98, s8, 8
	s_add_i32 s98, s98, s58
	v_and_or_b32 v236, v222, 15, s98
	v_lshlrev_b32_e32 v236, 2, v236
	global_load_dword v228, v236, s[22:23]
	global_load_dword v229, v236, s[22:23] offset:64
	global_load_dword v230, v236, s[22:23] offset:128
	global_load_dword v231, v236, s[22:23] offset:192
	global_load_dword v232, v236, s[22:23] offset:512
	global_load_dword v233, v236, s[22:23] offset:576
	global_load_dword v234, v236, s[22:23] offset:640
	global_load_dword v235, v236, s[22:23] offset:704

; __device__ __forceinline__ unsigned cvt_pk_bf16(float lo, float hi) { unsigned r; asm volatile("v_cvt_pk_bf16_f32 %0, %1, %2" : "=v"(r) : "v"(lo), "v"(hi)); return r; }
;     __device__ __forceinline__ void operator()(const f32x4 (&acc)[2][2][4][2], const Unit& u, int wr, int wc, int fr_, int fq_) const {
;     ...
;         const int col0 = colt + wc * 32 + 8 * fq, rowb = u.pm * BM + wr * 64 + fr;
;         float rs[2][4];
; #pragma unroll
;         for (int ai = 0; ai < 2; ++ai)
; #pragma unroll
;             for (int m = 0; m < 4; ++m) rs[ai][m] = rstd[rowb + ai * HALF + m * 16];
; #pragma unroll
;         for (int ai = 0; ai < 2; ++ai)
; #pragma unroll
;             for (int m = 0; m < 4; ++m) { const int row = rowb + ai * HALF + m * 16;
;                 if (base == proj && mode == 0) {
;                     const float sc = rs[ai][m] * (pn < 2 ? 0.125f : 1.0f); bf16_t* bp_ = (bf16_t*)proj + (size_t)row * 3584 + col0;
; #pragma unroll
;                     for (int bj = 0; bj < 2; ++bj) { const f32x4 v0 = acc[ai][bj][m][0] * sc, v1 = acc[ai][bj][m][1] * sc;
;                         u32x4 w; w.x = cvt_pk_bf16(v0[0], v0[1]); w.y = cvt_pk_bf16(v0[2], v0[3]); w.z = cvt_pk_bf16(v1[0], v1[1]); w.w = cvt_pk_bf16(v1[2], v1[3]); *(u32x4*)(bp_ + bj * HALF) = w; }
;                 } else {
;                 float* rp = base + (size_t)(row - rsub) * pitch + col0;
; #pragma unroll
;                 for (int bj = 0; bj < 2; ++bj)
; #pragma unroll
;                     for (int n = 0; n < 2; ++n) *(f32x4*)(rp + bj * HALF + n * 4) = acc[ai][bj][m][n] * rs[ai][m]; } }
.LBB0_827:
	s_lshl_b32 s37, s8, 8
	s_add_i32 s37, s37, s58
	v_and_or_b32 v164, v174, 15, s37
	v_ashrrev_i32_e32 v165, 31, v164
	v_lshl_add_u64 v[128:129], v[164:165], 2, s[22:23]
	s_waitcnt vmcnt(0)
	v_mov_b32_e32 v162, v228
	v_mov_b32_e32 v158, v229
	v_mov_b32_e32 v156, v230
	v_mov_b32_e32 v154, v231
	v_mov_b32_e32 v152, v232
	v_mov_b32_e32 v150, v233
	v_mov_b32_e32 v148, v234
	v_mov_b32_e32 v146, v235
	v_lshrrev_b32_e32 v128, 1, v174
	s_or_b32 s39, s9, s59
	v_and_or_b32 v160, v128, 24, s39
	s_cmp_lt_i32 s44, 2
	v_ashrrev_i32_e32 v161, 31, v160
	s_cselect_b64 s[6:7], -1, 0
	s_cmp_lg_u64 s[46:47], s[24:25]
	v_lshl_add_u64 v[128:129], v[160:161], 2, s[46:47]
	s_cselect_b64 s[46:47], -1, 0
	s_xor_b64 s[78:79], s[14:15], -1
	s_or_b64 s[46:47], s[78:79], s[46:47]
	s_mov_b64 s[48:49], -1
	s_and_b64 vcc, exec, s[46:47]
	s_cbranch_vccz .LBB0_829
	v_add_u32_e32 v130, s45, v164
	v_mad_i64_i32 v[130:131], s[48:49], s2, v130, 0
	v_lshl_add_u64 v[130:131], v[130:131], 2, v[128:129]
	s_waitcnt vmcnt(0)
	v_pk_mul_f32 v[168:169], v[126:127], v[162:163] op_sel_hi:[1,0]
	v_pk_mul_f32 v[166:167], v[124:125], v[162:163] op_sel_hi:[1,0]
	global_store_dwordx4 v[130:131], v[166:169], off
	s_mov_b64 s[48:49], 0
	s_nop 0
	v_pk_mul_f32 v[168:169], v[122:123], v[162:163] op_sel_hi:[1,0]
	v_pk_mul_f32 v[166:167], v[120:121], v[162:163] op_sel_hi:[1,0]
	global_store_dwordx4 v[130:131], v[166:169], off offset:16
	s_nop 1
	v_pk_mul_f32 v[168:169], v[118:119], v[162:163] op_sel_hi:[1,0]
	v_pk_mul_f32 v[166:167], v[116:117], v[162:163] op_sel_hi:[1,0]
	global_store_dwordx4 v[130:131], v[166:169], off offset:512
	s_nop 1
	v_pk_mul_f32 v[168:169], v[114:115], v[162:163] op_sel_hi:[1,0]
	v_pk_mul_f32 v[166:167], v[112:113], v[162:163] op_sel_hi:[1,0]
	global_store_dwordx4 v[130:131], v[166:169], off offset:528
